# RG_SPLIT 5 with the P7a order swap (tuning the RG-LRU tile split)
# baseline (speedup 1.0000x reference)
; #define RG_RAW_LOAD(tile_) do { _Pragma("unroll") for (int i = 0; i < 5; ++i) { const int q = tid + 512 * i, row = q >> 4, c16 = q & 15, tl = (tile_) * 128 - 3 + row; \
;         pre[i] = (q < 131 * 16 && tl >= 0) ? *(const u32x4*)(XR + ((size_t)b * SEQ + tl) * D + cb0 + c16 * 8) : (u32x4){0u, 0u, 0u, 0u}; } } while (0)
; #define RG_RAW_STORE() do { _Pragma("unroll") for (int i = 0; i < 5; ++i) { const int q = tid + 512 * i; if (q < 131 * 16) *(LAS u32x4*)(rawt + (q >> 4) * 136 + (q & 15) * 8) = pre[i]; } } while (0)
; __device__ __forceinline__ void rglru_task(const Params& P, LAS unsigned char* lds, int b, int n, int qd, int tid, int t0, int t1) {
;     ...
;     if (prompt) { RG_RAW_LOAD(t0); RG_RAW_STORE(); }
;     __syncthreads();
;     const int ntiles = t1;
;     for (int tile = t0; tile < ntiles; ++tile) {
;         const int row0 = prompt ? b * SEQ + tile * 128 : MPR;
;         if (prompt && tile + 1 < ntiles) RG_RAW_LOAD(tile + 1);
.LBB0_1296:
	s_or_b64 exec, exec, s[4:5]
	s_add_i32 s61, s61, 1
	s_cmp_eq_u32 s61, 5
	s_cbranch_scc1 .LBB0_1407
.LBB0_1297:
	s_lshl_b32 s64, s61, 7
	s_cmp_lt_u32 s61, 4
	s_cselect_b64 s[4:5], -1, 0
	s_and_b64 s[68:69], s[58:59], s[4:5]
	s_andn2_b64 vcc, exec, s[68:69]
	s_cbranch_vccnz .LBB0_1309
	s_or_b32 s6, s64, 0x7d
	v_add_u32_e32 v0, s6, v149
	s_waitcnt vmcnt(0)
	v_mov_b32_e32 v50, v68
	v_mov_b32_e32 v51, v68
	v_cmp_lt_i32_e32 vcc, -1, v0
	v_mov_b32_e32 v48, v68
	v_mov_b32_e32 v49, v68
	v_mov_b64_e32 v[54:55], v[50:51]
	s_and_b64 s[52:53], s[10:11], vcc
	v_mov_b64_e32 v[52:53], v[48:49]
	s_and_saveexec_b64 s[4:5], s[52:53]
	s_cbranch_execz .LBB0_1300
	v_mov_b32_e32 v1, v68
	v_lshlrev_b64 v[0:1], 11, v[0:1]
	v_lshl_add_u64 v[0:1], v[74:75], 0, v[0:1]
	global_load_dwordx4 v[52:55], v[0:1], off

; #define RG_RAW_LOAD(tile_) do { _Pragma("unroll") for (int i = 0; i < 5; ++i) { const int q = tid + 512 * i, row = q >> 4, c16 = q & 15, tl = (tile_) * 128 - 3 + row; \
;         pre[i] = (q < 131 * 16 && tl >= 0) ? *(const u32x4*)(XR + ((size_t)b * SEQ + tl) * D + cb0 + c16 * 8) : (u32x4){0u, 0u, 0u, 0u}; } } while (0)
; #define RG_RAW_STORE() do { _Pragma("unroll") for (int i = 0; i < 5; ++i) { const int q = tid + 512 * i; if (q < 131 * 16) *(LAS u32x4*)(rawt + (q >> 4) * 136 + (q & 15) * 8) = pre[i]; } } while (0)
; __device__ __forceinline__ void rglru_task(const Params& P, LAS unsigned char* lds, int b, int n, int qd, int tid, int t0, int t1) {
;     ...
;     if (prompt) { RG_RAW_LOAD(t0); RG_RAW_STORE(); }
.LBB0_1634:
	s_or_b64 exec, exec, s[12:13]
	s_lshl_b64 s[8:9], s[6:7], 22
	s_add_u32 s8, s10, s8
	s_addc_u32 s9, s11, s9
	s_lshl_b32 s10, s18, 1
	v_lshlrev_b32_e32 v2, 3, v0
	s_add_u32 s8, s8, s10
	v_and_b32_e32 v2, 0x78, v2
	s_addc_u32 s9, s9, 0
	v_lshlrev_b32_e32 v48, 1, v2
	v_lshl_add_u64 v[4:5], s[8:9], 0, v[48:49]
	s_mov_b64 s[8:9], 0x5040000
	v_lshl_add_u64 v[74:75], v[4:5], 0, s[8:9]
	v_ashrrev_i32_e32 v79, 4, v0
	s_movk_i32 s8, 0x830
	s_movk_i32 s12, 0xfc82
	v_cmp_gt_i32_e64 s[8:9], s8, v0
	v_cmp_lt_i32_e64 s[10:11], s12, v79
	s_and_b64 s[14:15], s[8:9], s[10:11]
	v_mov_b32_e32 v48, v49
	v_mov_b32_e32 v50, v49
	v_mov_b32_e32 v51, v49
	s_and_saveexec_b64 s[10:11], s[14:15]
	s_cbranch_execz .LBB0_1636
	v_add_u32_e32 v4, 0x27d, v79
	v_mov_b32_e32 v5, 0
	v_lshlrev_b64 v[4:5], 11, v[4:5]
	v_lshl_add_u64 v[4:5], v[74:75], 0, v[4:5]
	global_load_dwordx4 v[48:51], v[4:5], off
.LBB0_1636:
	s_or_b64 exec, exec, s[10:11]
	v_add_u32_e32 v3, 0x200, v0
	v_mov_b32_e32 v56, 0
	v_ashrrev_i32_e32 v80, 4, v3
	s_movk_i32 s10, 0x630
	v_mov_b32_e32 v57, v56
	v_cmp_gt_i32_e64 s[10:11], s10, v0
	v_cmp_lt_i32_e64 s[12:13], s12, v80
	v_mov_b32_e32 v58, v56
	v_mov_b32_e32 v59, v56
	v_mov_b64_e32 v[52:53], v[56:57]
	s_and_b64 s[14:15], s[10:11], s[12:13]
	v_mov_b64_e32 v[54:55], v[58:59]
	s_and_saveexec_b64 s[12:13], s[14:15]
	s_cbranch_execz .LBB0_1638
	v_add_u32_e32 v4, 0x27d, v80
	v_mov_b32_e32 v5, v56
	v_lshlrev_b64 v[4:5], 11, v[4:5]
	v_lshl_add_u64 v[4:5], v[74:75], 0, v[4:5]
	global_load_dwordx4 v[52:55], v[4:5], off
.LBB0_1638:
	s_or_b64 exec, exec, s[12:13]
	v_add_u32_e32 v3, 0x400, v0
	v_ashrrev_i32_e32 v81, 4, v3
	s_movk_i32 s12, 0x430
	s_movk_i32 s16, 0xfc82
	v_cmp_gt_i32_e64 s[12:13], s12, v0
	v_cmp_lt_i32_e64 s[14:15], s16, v81
	s_and_b64 s[18:19], s[12:13], s[14:15]
	s_and_saveexec_b64 s[14:15], s[18:19]
	s_cbranch_execz .LBB0_1640
	v_add_u32_e32 v4, 0x27d, v81
	v_mov_b32_e32 v5, 0
	v_lshlrev_b64 v[4:5], 11, v[4:5]
	v_lshl_add_u64 v[4:5], v[74:75], 0, v[4:5]
	global_load_dwordx4 v[56:59], v[4:5], off
.LBB0_1640:
	s_or_b64 exec, exec, s[14:15]
	v_add_u32_e32 v3, 0x600, v0
	v_mov_b32_e32 v64, 0
	v_ashrrev_i32_e32 v82, 4, v3
	s_movk_i32 s14, 0x230
	v_mov_b32_e32 v65, v64
	v_cmp_gt_i32_e64 s[14:15], s14, v0
	v_cmp_lt_i32_e64 s[16:17], s16, v82
	v_mov_b32_e32 v66, v64
	v_mov_b32_e32 v67, v64
	v_mov_b64_e32 v[60:61], v[64:65]
	s_and_b64 s[18:19], s[14:15], s[16:17]
	v_mov_b64_e32 v[62:63], v[66:67]
	s_and_saveexec_b64 s[16:17], s[18:19]
	s_cbranch_execz .LBB0_1642
	v_add_u32_e32 v4, 0x27d, v82
	v_mov_b32_e32 v5, 0
	v_lshlrev_b64 v[4:5], 11, v[4:5]
	v_lshl_add_u64 v[4:5], v[74:75], 0, v[4:5]
	global_load_dwordx4 v[60:63], v[4:5], off
.LBB0_1642:
	s_or_b64 exec, exec, s[16:17]
	v_add_u32_e32 v3, 0x800, v0
	v_ashrrev_i32_e32 v83, 4, v3
	s_movk_i32 s18, 0xfc82
	v_cmp_gt_i32_e64 s[16:17], 48, v0
	v_cmp_lt_i32_e64 s[18:19], s18, v83
	s_and_b64 s[20:21], s[16:17], s[18:19]
	v_mov_b32_e32 v65, 0
	v_mov_b32_e32 v66, 0
	v_mov_b32_e32 v67, 0
	s_and_saveexec_b64 s[18:19], s[20:21]
	s_cbranch_execz .LBB0_1644
	v_add_u32_e32 v4, 0x27d, v83
	v_mov_b32_e32 v5, 0
	v_lshlrev_b64 v[4:5], 11, v[4:5]
	v_lshl_add_u64 v[4:5], v[74:75], 0, v[4:5]
	global_load_dwordx4 v[64:67], v[4:5], off

; __device__ __forceinline__ float softplus_f(float x) { return x > 20.f ? x : log1pf(__expf(x)); }
; __device__ __forceinline__ unsigned char* karg_ws() { return *(volatile KAS ucptr_t*)((const KAS char*)__builtin_amdgcn_kernarg_segment_ptr() + 264); }
; #define INP(k) karg_in(k)
; #define RG_RAW_LOAD(tile_) do { _Pragma("unroll") for (int i = 0; i < 5; ++i) { const int q = tid + 512 * i, row = q >> 4, c16 = q & 15, tl = (tile_) * 128 - 3 + row; \
;         pre[i] = (q < 131 * 16 && tl >= 0) ? *(const u32x4*)(XR + ((size_t)b * SEQ + tl) * D + cb0 + c16 * 8) : (u32x4){0u, 0u, 0u, 0u}; } } while (0)
; #define RG_RAW_STORE() do { _Pragma("unroll") for (int i = 0; i < 5; ++i) { const int q = tid + 512 * i; if (q < 131 * 16) *(LAS u32x4*)(rawt + (q >> 4) * 136 + (q & 15) * 8) = pre[i]; } } while (0)
; #define lane opq(lane_now())
; #define tid opq((wave << 6) | lane_now())
; __device__ __forceinline__ void rglru_task(const Params& P, LAS unsigned char* lds, int b, int n, int qd, int tid, int t0, int t1) {
;     ...
;     const int cb0 = n * 128, oc0 = cb0 + qd * 32;
;     const bool prompt = b >= 0;
;     for (int i = tid; i < 640; i += NTHR) cw[i] = i < 512 ? INP(15)[(size_t)(i >> 7) * D + cb0 + (i & 127)] : INP(16)[cb0 + (i - 512)];
;     if (tid < 32) hc[tid] = t0 > 0 ? ((const float*)(karg_ws() + WS_HCARRY))[(size_t)b * D + oc0 + tid] : 0.f;
;     const int tb = wave & 3, cbk = wave >> 2;
;     bf16x8 Bf[8];
;     { const bf16* wrow = WRG + (size_t)(n * 256 + cbk * 128 + qd * 32 + (lane & 31)) * 128 + (lane >> 5) * 8;
; #pragma unroll
;       for (int ks = 0; ks < 8; ++ks) Bf[ks] = *(const bf16x8*)(wrow + ks * 16); }
;     const float gbias = INP(cbk ? 20 : 18)[oc0 + (lane & 31)];
;     const int ch = tid & 31, seg = tid >> 5;
;     const float sp = softplus_f(-INP(21)[oc0 + ch]);
;     float hlast = 0.f;
;     u32x4 pre[5];
;     ...
;     if (prompt) { RG_RAW_LOAD(t0); RG_RAW_STORE(); }
;     __syncthreads();
;     const int ntiles = t1;
;     for (int tile = t0; tile < ntiles; ++tile) {
.LBB0_1651:
	s_or_b64 exec, exec, s[18:19]
	v_lshrrev_b32_e32 v4, 1, v0
	v_and_b32_e32 v10, 0x60, v4
	s_add_i32 s20, 0, 0xc800
	s_lshl_b32 s65, s6, 11
	v_or_b32_e32 v4, v10, v72
	s_add_i32 s57, 0, 0x10800
	v_mov_b32_e32 v5, s20
	s_add_i32 s58, 0, 0x14800
	s_add_i32 s59, 0, 0x15000
	s_add_i32 s63, 0, 0x15800
	s_lshl_b32 s20, s64, 1
	v_mul_u32_u24_e32 v11, 0x110, v4
	v_mov_b32_e32 v4, s57
	v_mov_b32_e32 v68, 0
	s_add_u32 s4, s4, s20
	v_cndmask_b32_e32 v12, v4, v5, vcc
	s_addc_u32 s5, s5, 0
	v_lshlrev_b32_e32 v4, 1, v72
	v_mov_b32_e32 v5, v68
	v_lshlrev_b32_e32 v13, 2, v72
	v_lshl_add_u64 v[4:5], s[4:5], 0, v[4:5]
	s_mov_b64 s[4:5], 0x7080000
	v_lshl_add_u64 v[76:77], v[4:5], 0, s[4:5]
	v_or_b32_e32 v4, 0x80, v13
	v_add_u32_e32 v89, s58, v4
	v_add_u32_e32 v90, s59, v4
	v_or_b32_e32 v4, 0x100, v13
	v_add_u32_e32 v91, s58, v4
	v_add_u32_e32 v92, s59, v4
	v_or_b32_e32 v4, 0x180, v13
	v_add_u32_e32 v93, s58, v4
	v_add_u32_e32 v94, s59, v4
	v_or_b32_e32 v4, 0x200, v13
	v_add_u32_e32 v95, s58, v4
	v_add_u32_e32 v96, s59, v4
	v_or_b32_e32 v4, 0x280, v13
	v_add_u32_e32 v97, s58, v4
	v_add_u32_e32 v98, s59, v4
	v_or_b32_e32 v4, 0x300, v13
	v_add_u32_e32 v99, s58, v4
	v_add_u32_e32 v100, s59, v4
	v_or_b32_e32 v4, 0x380, v13
	v_add_u32_e32 v101, s58, v4
	v_add_u32_e32 v102, s59, v4
	v_or_b32_e32 v4, 0x400, v13
	v_add_u32_e32 v103, s58, v4
	v_add_u32_e32 v104, s59, v4
	v_or_b32_e32 v4, 0x480, v13
	v_add_u32_e32 v105, s58, v4
	v_add_u32_e32 v106, s59, v4
	v_or_b32_e32 v4, 0x500, v13
	v_add_u32_e32 v107, s58, v4
	v_add_u32_e32 v108, s59, v4
	v_or_b32_e32 v4, 0x580, v13
	v_add_u32_e32 v109, s58, v4
	v_add_u32_e32 v110, s59, v4
	v_or_b32_e32 v4, 0x600, v13
	v_ashrrev_i32_e32 v6, 5, v0
	v_add_u32_e32 v111, s58, v4
	v_add_u32_e32 v112, s59, v4
	v_or_b32_e32 v4, 0x680, v13
	v_lshlrev_b32_e32 v85, 3, v6
	v_add_u32_e32 v113, s58, v4
	v_add_u32_e32 v114, s59, v4
	v_or_b32_e32 v4, 0x700, v13
	v_add_u32_e32 v115, s58, v4
	v_add_u32_e32 v116, s59, v4
	v_or_b32_e32 v119, 1, v85
	v_lshl_or_b32 v4, v6, 10, v13
	v_or_b32_e32 v120, 2, v85
	v_add_u32_e32 v126, 0, v4
	v_add_u32_e32 v127, s57, v4
	v_lshl_or_b32 v4, v119, 7, v13
	v_or_b32_e32 v121, 3, v85
	v_add_u32_e32 v128, 0, v4
	v_add_u32_e32 v129, s57, v4
	v_lshl_or_b32 v4, v120, 7, v13
	v_or_b32_e32 v122, 4, v85
	v_add_u32_e32 v130, 0, v4
	v_add_u32_e32 v131, s57, v4
	v_lshl_or_b32 v4, v121, 7, v13
	v_or_b32_e32 v123, 5, v85
	v_add_u32_e32 v132, 0, v4
	v_add_u32_e32 v133, s57, v4
	v_lshl_or_b32 v4, v122, 7, v13
	v_or_b32_e32 v124, 6, v85
	v_add_u32_e32 v134, 0, v4
	v_add_u32_e32 v135, s57, v4
	v_lshl_or_b32 v4, v123, 7, v13
	v_ashrrev_i32_e32 v7, 2, v0
	v_and_b32_e32 v8, 3, v0
	v_lshlrev_b32_e32 v0, 2, v0
	v_or_b32_e32 v125, 7, v85
	v_add_u32_e32 v136, 0, v4
	v_add_u32_e32 v137, s57, v4
	v_lshl_or_b32 v4, v124, 7, v13
	v_add_u32_e32 v86, s58, v0
	v_add_u32_e32 v87, s59, v0
	v_lshlrev_b32_e32 v0, 9, v1
	v_add_u32_e32 v138, 0, v4
	v_add_u32_e32 v139, s57, v4
	v_lshl_or_b32 v4, v125, 7, v13
	v_lshl_add_u32 v3, v3, 1, 0
	v_mul_lo_u32 v9, v7, s54
	v_cmp_eq_u32_e64 s[20:21], 15, v6
	v_lshlrev_b32_e32 v1, 7, v10
	v_add3_u32 v0, v12, v13, v0
	v_cmp_lt_i32_e64 s[22:23], 0, v6
	v_cmp_lt_i32_e64 s[24:25], 1, v6
	v_cmp_lt_i32_e64 s[26:27], 2, v6
	v_cmp_lt_i32_e64 s[28:29], 3, v6
	v_cmp_lt_i32_e64 s[30:31], 4, v6
	v_cmp_lt_i32_e64 s[34:35], 5, v6
	v_cmp_lt_i32_e64 s[36:37], 6, v6
	v_cmp_lt_i32_e64 s[38:39], 7, v6
	v_cmp_lt_i32_e64 s[40:41], 8, v6
	v_cmp_lt_i32_e64 s[42:43], 9, v6
	v_cmp_lt_i32_e64 s[44:45], 10, v6
	v_cmp_lt_i32_e64 s[46:47], 11, v6
	v_cmp_lt_i32_e64 s[48:49], 12, v6
	v_cmp_lt_i32_e64 s[50:51], 13, v6
	v_cmp_lt_i32_e64 s[52:53], 14, v6
	v_add_u32_e32 v140, 0, v4
	v_add_u32_e32 v141, s57, v4
	v_mul_lo_u32 v4, v79, s54
	v_mul_lo_u32 v5, v80, s54
	v_mul_lo_u32 v6, v81, s54
	v_mul_lo_u32 v10, v82, s54
	v_mov_b32_e32 v12, 0x8800
	v_cmp_eq_u32_e64 s[18:19], s3, v8
	v_add_u32_e32 v88, s63, v13
	s_mov_b32 s68, 5
	v_add_u32_e32 v117, s59, v13
	v_add_u32_e32 v118, s58, v13
	v_lshlrev_b32_e32 v142, 7, v8
	v_lshl_add_u32 v143, v7, 7, v12
	v_lshl_add_u32 v144, v8, 6, v9
	v_add_u32_e32 v145, v3, v11
	v_add_u32_e32 v146, v0, v1
	v_mov_b32_e32 v147, 0x3c088889
	s_mov_b32 s66, 0xbe99999a
	v_add_u32_e32 v148, v2, v4
	v_add_u32_e32 v149, v2, v5
	v_add_u32_e32 v150, v2, v6
	v_add_u32_e32 v151, v2, v10
	s_waitcnt lgkmcnt(0)
	s_barrier
	s_branch .LBB0_1653

; #define RG_RAW_LOAD(tile_) do { _Pragma("unroll") for (int i = 0; i < 5; ++i) { const int q = tid + 512 * i, row = q >> 4, c16 = q & 15, tl = (tile_) * 128 - 3 + row; \
;         pre[i] = (q < 131 * 16 && tl >= 0) ? *(const u32x4*)(XR + ((size_t)b * SEQ + tl) * D + cb0 + c16 * 8) : (u32x4){0u, 0u, 0u, 0u}; } } while (0)
; #define RG_RAW_STORE() do { _Pragma("unroll") for (int i = 0; i < 5; ++i) { const int q = tid + 512 * i; if (q < 131 * 16) *(LAS u32x4*)(rawt + (q >> 4) * 136 + (q & 15) * 8) = pre[i]; } } while (0)
; __device__ __forceinline__ void rglru_task(const Params& P, LAS unsigned char* lds, int b, int n, int qd, int tid, int t0, int t1) {
;     ...
;     if (prompt) { RG_RAW_LOAD(t0); RG_RAW_STORE(); }
.LBB0_1706:
	s_or_b64 exec, exec, s[14:15]
	s_lshl_b32 s7, s56, 17
	s_add_u32 s7, s10, s7
	s_addc_u32 s10, s11, 0
	s_lshl_b64 s[8:9], s[12:13], 1
	v_lshlrev_b32_e32 v2, 3, v0
	s_add_u32 s8, s7, s8
	v_and_b32_e32 v2, 0x78, v2
	s_addc_u32 s9, s10, s9
	v_lshlrev_b32_e32 v48, 1, v2
	v_lshl_add_u64 v[4:5], s[8:9], 0, v[48:49]
	s_mov_b64 s[8:9], 0x5040000
	s_movk_i32 s7, 0x830
	v_lshl_add_u64 v[74:75], v[4:5], 0, s[8:9]
	v_ashrrev_i32_e32 v79, 4, v0
	v_cmp_gt_i32_e64 s[8:9], s7, v0
	s_movk_i32 s7, 0xfc82
	v_cmp_lt_i32_e64 s[10:11], s7, v79
	s_and_b64 s[12:13], s[8:9], s[10:11]
	v_mov_b32_e32 v48, v49
	v_mov_b32_e32 v50, v49
	v_mov_b32_e32 v51, v49
	s_and_saveexec_b64 s[10:11], s[12:13]
	s_cbranch_execz .LBB0_1708
	v_add_u32_e32 v4, 0x27d, v79
	v_mov_b32_e32 v5, 0
	v_lshlrev_b64 v[4:5], 11, v[4:5]
	v_lshl_add_u64 v[4:5], v[74:75], 0, v[4:5]
	global_load_dwordx4 v[48:51], v[4:5], off
.LBB0_1708:
	s_or_b64 exec, exec, s[10:11]
	v_add_u32_e32 v3, 0x200, v0
	v_mov_b32_e32 v56, 0
	v_ashrrev_i32_e32 v80, 4, v3
	s_movk_i32 s10, 0x630
	v_mov_b32_e32 v57, v56
	v_cmp_gt_i32_e64 s[10:11], s10, v0
	v_cmp_lt_i32_e64 s[12:13], s7, v80
	v_mov_b32_e32 v58, v56
	v_mov_b32_e32 v59, v56
	v_mov_b64_e32 v[52:53], v[56:57]
	s_and_b64 s[14:15], s[10:11], s[12:13]
	v_mov_b64_e32 v[54:55], v[58:59]
	s_and_saveexec_b64 s[12:13], s[14:15]
	s_cbranch_execz .LBB0_1710
	v_add_u32_e32 v4, 0x27d, v80
	v_mov_b32_e32 v5, v56
	v_lshlrev_b64 v[4:5], 11, v[4:5]
	v_lshl_add_u64 v[4:5], v[74:75], 0, v[4:5]
	global_load_dwordx4 v[52:55], v[4:5], off
.LBB0_1710:
	s_or_b64 exec, exec, s[12:13]
	v_add_u32_e32 v3, 0x400, v0
	s_movk_i32 s7, 0x430
	v_ashrrev_i32_e32 v81, 4, v3
	v_cmp_gt_i32_e64 s[12:13], s7, v0
	s_movk_i32 s7, 0xfc82
	v_cmp_lt_i32_e64 s[14:15], s7, v81
	s_and_b64 s[16:17], s[12:13], s[14:15]
	s_and_saveexec_b64 s[14:15], s[16:17]
	s_cbranch_execz .LBB0_1712
	v_add_u32_e32 v4, 0x27d, v81
	v_mov_b32_e32 v5, 0
	v_lshlrev_b64 v[4:5], 11, v[4:5]
	v_lshl_add_u64 v[4:5], v[74:75], 0, v[4:5]
	global_load_dwordx4 v[56:59], v[4:5], off
.LBB0_1712:
	s_or_b64 exec, exec, s[14:15]
	v_add_u32_e32 v3, 0x600, v0
	v_mov_b32_e32 v64, 0
	v_ashrrev_i32_e32 v82, 4, v3
	s_movk_i32 s14, 0x230
	v_mov_b32_e32 v65, v64
	v_cmp_gt_i32_e64 s[14:15], s14, v0
	v_cmp_lt_i32_e64 s[16:17], s7, v82
	v_mov_b32_e32 v66, v64
	v_mov_b32_e32 v67, v64
	v_mov_b64_e32 v[60:61], v[64:65]
	s_and_b64 s[18:19], s[14:15], s[16:17]
	v_mov_b64_e32 v[62:63], v[66:67]
	s_and_saveexec_b64 s[16:17], s[18:19]
	s_cbranch_execz .LBB0_1714
	v_add_u32_e32 v4, 0x27d, v82
	v_mov_b32_e32 v5, 0
	v_lshlrev_b64 v[4:5], 11, v[4:5]
	v_lshl_add_u64 v[4:5], v[74:75], 0, v[4:5]
	global_load_dwordx4 v[60:63], v[4:5], off

; __device__ __forceinline__ float softplus_f(float x) { return x > 20.f ? x : log1pf(__expf(x)); }
; __device__ __forceinline__ unsigned char* karg_ws() { return *(volatile KAS ucptr_t*)((const KAS char*)__builtin_amdgcn_kernarg_segment_ptr() + 264); }
; #define INP(k) karg_in(k)
; #define RG_RAW_LOAD(tile_) do { _Pragma("unroll") for (int i = 0; i < 5; ++i) { const int q = tid + 512 * i, row = q >> 4, c16 = q & 15, tl = (tile_) * 128 - 3 + row; \
;         pre[i] = (q < 131 * 16 && tl >= 0) ? *(const u32x4*)(XR + ((size_t)b * SEQ + tl) * D + cb0 + c16 * 8) : (u32x4){0u, 0u, 0u, 0u}; } } while (0)
; #define RG_RAW_STORE() do { _Pragma("unroll") for (int i = 0; i < 5; ++i) { const int q = tid + 512 * i; if (q < 131 * 16) *(LAS u32x4*)(rawt + (q >> 4) * 136 + (q & 15) * 8) = pre[i]; } } while (0)
; #define lane opq(lane_now())
; #define tid opq((wave << 6) | lane_now())
; __device__ __forceinline__ void rglru_task(const Params& P, LAS unsigned char* lds, int b, int n, int qd, int tid, int t0, int t1) {
;     ...
;     const int cb0 = n * 128, oc0 = cb0 + qd * 32;
;     const bool prompt = b >= 0;
;     for (int i = tid; i < 640; i += NTHR) cw[i] = i < 512 ? INP(15)[(size_t)(i >> 7) * D + cb0 + (i & 127)] : INP(16)[cb0 + (i - 512)];
;     if (tid < 32) hc[tid] = t0 > 0 ? ((const float*)(karg_ws() + WS_HCARRY))[(size_t)b * D + oc0 + tid] : 0.f;
;     const int tb = wave & 3, cbk = wave >> 2;
;     bf16x8 Bf[8];
;     { const bf16* wrow = WRG + (size_t)(n * 256 + cbk * 128 + qd * 32 + (lane & 31)) * 128 + (lane >> 5) * 8;
; #pragma unroll
;       for (int ks = 0; ks < 8; ++ks) Bf[ks] = *(const bf16x8*)(wrow + ks * 16); }
;     const float gbias = INP(cbk ? 20 : 18)[oc0 + (lane & 31)];
;     const int ch = tid & 31, seg = tid >> 5;
;     const float sp = softplus_f(-INP(21)[oc0 + ch]);
;     float hlast = 0.f;
;     u32x4 pre[5];
;     ...
;     if (prompt) { RG_RAW_LOAD(t0); RG_RAW_STORE(); }
;     __syncthreads();
;     const int ntiles = t1;
;     for (int tile = t0; tile < ntiles; ++tile) {
.LBB0_1722:
	s_or_b64 exec, exec, s[18:19]
	v_lshrrev_b32_e32 v4, 1, v0
	s_mov_b32 s7, 0
	v_and_b32_e32 v8, 3, v0
	v_and_b32_e32 v10, 0x60, v4
	s_lshl_b32 s61, s56, 6
	v_cmp_eq_u32_e64 s[18:19], s3, v8
	v_or_b32_e32 v4, v10, v72
	s_add_i32 s3, 0, 0xc800
	s_lshl_b64 s[20:21], s[6:7], 1
	v_mul_u32_u24_e32 v11, 0x110, v4
	v_mov_b32_e32 v4, s57
	v_mov_b32_e32 v5, s3
	v_mov_b32_e32 v68, 0
	s_add_u32 s4, s4, s20
	v_cndmask_b32_e32 v12, v4, v5, vcc
	s_addc_u32 s5, s5, s21
	v_lshlrev_b32_e32 v4, 1, v72
	v_mov_b32_e32 v5, v68
	v_lshlrev_b32_e32 v13, 2, v72
	v_lshl_add_u64 v[4:5], s[4:5], 0, v[4:5]
	s_mov_b64 s[4:5], 0x7080000
	v_lshl_add_u64 v[76:77], v[4:5], 0, s[4:5]
	v_or_b32_e32 v4, 0x80, v13
	v_add_u32_e32 v89, s58, v4
	v_add_u32_e32 v90, s59, v4
	v_or_b32_e32 v4, 0x100, v13
	v_add_u32_e32 v91, s58, v4
	v_add_u32_e32 v92, s59, v4
	v_or_b32_e32 v4, 0x180, v13
	v_add_u32_e32 v93, s58, v4
	v_add_u32_e32 v94, s59, v4
	v_or_b32_e32 v4, 0x200, v13
	v_add_u32_e32 v95, s58, v4
	v_add_u32_e32 v96, s59, v4
	v_or_b32_e32 v4, 0x280, v13
	v_add_u32_e32 v97, s58, v4
	v_add_u32_e32 v98, s59, v4
	v_or_b32_e32 v4, 0x300, v13
	v_add_u32_e32 v99, s58, v4
	v_add_u32_e32 v100, s59, v4
	v_or_b32_e32 v4, 0x380, v13
	v_add_u32_e32 v101, s58, v4
	v_add_u32_e32 v102, s59, v4
	v_or_b32_e32 v4, 0x400, v13
	v_add_u32_e32 v103, s58, v4
	v_add_u32_e32 v104, s59, v4
	v_or_b32_e32 v4, 0x480, v13
	v_add_u32_e32 v105, s58, v4
	v_add_u32_e32 v106, s59, v4
	v_or_b32_e32 v4, 0x500, v13
	v_add_u32_e32 v107, s58, v4
	v_add_u32_e32 v108, s59, v4
	v_or_b32_e32 v4, 0x580, v13
	v_add_u32_e32 v109, s58, v4
	v_add_u32_e32 v110, s59, v4
	v_or_b32_e32 v4, 0x600, v13
	v_ashrrev_i32_e32 v6, 5, v0
	v_add_u32_e32 v111, s58, v4
	v_add_u32_e32 v112, s59, v4
	v_or_b32_e32 v4, 0x680, v13
	v_lshlrev_b32_e32 v85, 3, v6
	v_add_u32_e32 v113, s58, v4
	v_add_u32_e32 v114, s59, v4
	v_or_b32_e32 v4, 0x700, v13
	v_add_u32_e32 v115, s58, v4
	v_add_u32_e32 v116, s59, v4
	v_or_b32_e32 v119, 1, v85
	v_lshl_or_b32 v4, v6, 10, v13
	v_or_b32_e32 v120, 2, v85
	v_add_u32_e32 v126, 0, v4
	v_add_u32_e32 v127, s57, v4
	v_lshl_or_b32 v4, v119, 7, v13
	v_or_b32_e32 v121, 3, v85
	v_add_u32_e32 v128, 0, v4
	v_add_u32_e32 v129, s57, v4
	v_lshl_or_b32 v4, v120, 7, v13
	v_or_b32_e32 v122, 4, v85
	v_add_u32_e32 v130, 0, v4
	v_add_u32_e32 v131, s57, v4
	v_lshl_or_b32 v4, v121, 7, v13
	v_or_b32_e32 v123, 5, v85
	v_add_u32_e32 v132, 0, v4
	v_add_u32_e32 v133, s57, v4
	v_lshl_or_b32 v4, v122, 7, v13
	v_or_b32_e32 v124, 6, v85
	v_add_u32_e32 v134, 0, v4
	v_add_u32_e32 v135, s57, v4
	v_lshl_or_b32 v4, v123, 7, v13
	v_ashrrev_i32_e32 v7, 2, v0
	v_lshlrev_b32_e32 v0, 2, v0
	v_or_b32_e32 v125, 7, v85
	v_add_u32_e32 v136, 0, v4
	v_add_u32_e32 v137, s57, v4
	v_lshl_or_b32 v4, v124, 7, v13
	v_add_u32_e32 v86, s58, v0
	v_add_u32_e32 v87, s59, v0
	v_lshlrev_b32_e32 v0, 9, v1
	v_add_u32_e32 v138, 0, v4
	v_add_u32_e32 v139, s57, v4
	v_lshl_or_b32 v4, v125, 7, v13
	v_lshl_add_u32 v3, v3, 1, 0
	v_mul_lo_u32 v9, v7, s54
	v_cmp_eq_u32_e64 s[20:21], 15, v6
	v_lshlrev_b32_e32 v1, 7, v10
	v_add3_u32 v0, v12, v13, v0
	v_cmp_lt_i32_e64 s[22:23], 0, v6
	v_cmp_lt_i32_e64 s[24:25], 1, v6
	v_cmp_lt_i32_e64 s[26:27], 2, v6
	v_cmp_lt_i32_e64 s[28:29], 3, v6
	v_cmp_lt_i32_e64 s[30:31], 4, v6
	v_cmp_lt_i32_e64 s[34:35], 5, v6
	v_cmp_lt_i32_e64 s[36:37], 6, v6
	v_cmp_lt_i32_e64 s[38:39], 7, v6
	v_cmp_lt_i32_e64 s[40:41], 8, v6
	v_cmp_lt_i32_e64 s[42:43], 9, v6
	v_cmp_lt_i32_e64 s[44:45], 10, v6
	v_cmp_lt_i32_e64 s[46:47], 11, v6
	v_cmp_lt_i32_e64 s[48:49], 12, v6
	v_cmp_lt_i32_e64 s[50:51], 13, v6
	v_cmp_lt_i32_e64 s[52:53], 14, v6
	v_add_u32_e32 v140, 0, v4
	v_add_u32_e32 v141, s57, v4
	v_mul_lo_u32 v4, v79, s54
	v_mul_lo_u32 v5, v80, s54
	v_mul_lo_u32 v6, v81, s54
	v_mul_lo_u32 v10, v82, s54
	v_mov_b32_e32 v12, 0x8800
	v_add_u32_e32 v88, s63, v13
	s_mov_b32 s65, 5
	v_add_u32_e32 v117, s59, v13
	v_add_u32_e32 v118, s58, v13
	v_lshlrev_b32_e32 v142, 7, v8
	v_lshl_add_u32 v143, v7, 7, v12
	v_lshl_add_u32 v144, v8, 6, v9
	v_add_u32_e32 v145, v3, v11
	v_add_u32_e32 v146, v0, v1
	v_mov_b32_e32 v147, 0x3c088889
	s_mov_b32 s3, 0xbe99999a
	v_add_u32_e32 v148, v2, v4
	v_add_u32_e32 v149, v2, v5
	v_add_u32_e32 v150, v2, v6
	v_add_u32_e32 v151, v2, v10
	s_waitcnt lgkmcnt(0)
	s_barrier
	s_branch .LBB0_1724

; #define RG_RAW_LOAD(tile_) do { _Pragma("unroll") for (int i = 0; i < 5; ++i) { const int q = tid + 512 * i, row = q >> 4, c16 = q & 15, tl = (tile_) * 128 - 3 + row; \
;         pre[i] = (q < 131 * 16 && tl >= 0) ? *(const u32x4*)(XR + ((size_t)b * SEQ + tl) * D + cb0 + c16 * 8) : (u32x4){0u, 0u, 0u, 0u}; } } while (0)
; #define RG_RAW_STORE() do { _Pragma("unroll") for (int i = 0; i < 5; ++i) { const int q = tid + 512 * i; if (q < 131 * 16) *(LAS u32x4*)(rawt + (q >> 4) * 136 + (q & 15) * 8) = pre[i]; } } while (0)
; __device__ __forceinline__ void rglru_task(const Params& P, LAS unsigned char* lds, int b, int n, int qd, int tid, int t0, int t1) {
;     ...
;     if (prompt) { RG_RAW_LOAD(t0); RG_RAW_STORE(); }
.LBB0_1879:
	v_add_u32_e32 v4, 0x27d, v83
	v_mov_b32_e32 v5, 0
	v_lshlrev_b64 v[4:5], 11, v[4:5]
	v_lshl_add_u64 v[4:5], v[74:75], 0, v[4:5]
	global_load_dwordx4 v[64:67], v[4:5], off
	s_or_b64 exec, exec, s[18:19]
	v_lshl_add_u32 v2, v2, 1, s62
	s_and_saveexec_b64 s[18:19], s[8:9]
	s_cbranch_execz .LBB0_1716
